# LRU pass A: direction-1 gate MFMAs and their LDS reads issued inside direction-0 gate math (latency covered by VALU work)
# baseline (speedup 1.0000x reference)
.LBB0_351:
	s_mul_i32 s7, s4, 0x4a40
	v_add_u32_e32 v52, s7, v95
	v_add_u32_e32 v4, v52, v98
	v_add_u32_e32 v58, 0x8800, v4
	ds_read_b128 v[0:3], v94 offset:32768
	ds_read2_b64 v[4:7], v58 offset1:18
	ds_read_b128 v[8:11], v94 offset:33024
	ds_read_b128 v[12:15], v94 offset:33280
	ds_read_b128 v[16:19], v94 offset:33536
	ds_read_b128 v[20:23], v94 offset:33792
	s_waitcnt lgkmcnt(4)
	v_lshlrev_b32_e32 v28, 16, v4
	v_and_b32_e32 v29, 0xffff0000, v4
	v_add_u32_e32 v4, v52, v99
	v_lshlrev_b32_e32 v30, 16, v5
	v_and_b32_e32 v31, 0xffff0000, v5
	ds_read_b64 v[4:5], v4 offset:34816
	v_lshlrev_b32_e32 v48, 16, v6
	v_and_b32_e32 v49, 0xffff0000, v6
	v_lshlrev_b32_e32 v50, 16, v7
	v_and_b32_e32 v51, 0xffff0000, v7
	s_waitcnt lgkmcnt(0)
	v_lshlrev_b32_e32 v54, 16, v4
	v_and_b32_e32 v55, 0xffff0000, v4
	v_lshlrev_b32_e32 v56, 16, v5
	v_and_b32_e32 v57, 0xffff0000, v5
	ds_read2_b64 v[4:7], v58 offset0:90 offset1:108
	ds_read2_b64 v[24:27], v58 offset0:36 offset1:72
	v_add_u32_e32 v72, 0x800, v104
	v_and_b32_e32 v114, 64, v180
	v_xor_b32_e32 v116, 32, v180
	s_waitcnt lgkmcnt(1)
	v_lshlrev_b32_e32 v60, 16, v4
	v_and_b32_e32 v61, 0xffff0000, v4
	v_lshlrev_b32_e32 v62, 16, v5
	v_and_b32_e32 v63, 0xffff0000, v5
	v_lshlrev_b32_e32 v68, 16, v6
	v_and_b32_e32 v69, 0xffff0000, v6
	v_lshlrev_b32_e32 v70, 16, v7
	v_and_b32_e32 v71, 0xffff0000, v7
	v_pk_fma_f32 v[4:5], v[0:1], v[28:29], v[20:21]
	v_pk_fma_f32 v[6:7], v[2:3], v[30:31], v[22:23]
	s_waitcnt lgkmcnt(0)
	v_lshlrev_b32_e32 v52, 16, v24
	v_and_b32_e32 v53, 0xffff0000, v24
	v_lshlrev_b32_e32 v24, 16, v25
	v_and_b32_e32 v25, 0xffff0000, v25
	v_pk_fma_f32 v[6:7], v[10:11], v[50:51], v[6:7]
	v_pk_fma_f32 v[4:5], v[8:9], v[48:49], v[4:5]
	v_pk_fma_f32 v[6:7], v[14:15], v[24:25], v[6:7]
	v_pk_fma_f32 v[4:5], v[12:13], v[52:53], v[4:5]
	v_pk_fma_f32 v[6:7], v[18:19], v[56:57], v[6:7]
	v_pk_fma_f32 v[4:5], v[16:17], v[54:55], v[4:5]
	ds_write_b128 v101, v[4:7]
	v_cvt_pk_bf16_f32 v4, v4, v5
	v_cvt_pk_bf16_f32 v5, v6, v7
	v_add_u32_e32 v28, v96, v98
	ds_write_b64 v28, v[4:5]
	v_pk_fma_f32 v[4:5], v[0:1], v[48:49], v[20:21]
	v_pk_fma_f32 v[6:7], v[2:3], v[50:51], v[22:23]
	v_pk_fma_f32 v[4:5], v[8:9], v[52:53], v[4:5]
	v_pk_fma_f32 v[6:7], v[10:11], v[24:25], v[6:7]
	v_lshlrev_b32_e32 v58, 16, v26
	v_and_b32_e32 v59, 0xffff0000, v26
	v_lshlrev_b32_e32 v26, 16, v27
	v_and_b32_e32 v27, 0xffff0000, v27
	v_pk_fma_f32 v[4:5], v[12:13], v[54:55], v[4:5]
	v_pk_fma_f32 v[6:7], v[14:15], v[56:57], v[6:7]
	v_pk_fma_f32 v[4:5], v[16:17], v[58:59], v[4:5]
	v_pk_fma_f32 v[6:7], v[18:19], v[26:27], v[6:7]
	ds_write_b128 v101, v[4:7] offset:272
	v_cvt_pk_bf16_f32 v4, v4, v5
	v_cvt_pk_bf16_f32 v5, v6, v7
	ds_write_b64 v28, v[4:5] offset:144
	v_pk_fma_f32 v[4:5], v[0:1], v[52:53], v[20:21]
	v_pk_fma_f32 v[6:7], v[2:3], v[24:25], v[22:23]
	v_pk_fma_f32 v[0:1], v[0:1], v[54:55], v[20:21]
	v_pk_fma_f32 v[2:3], v[2:3], v[56:57], v[22:23]
	v_pk_fma_f32 v[6:7], v[10:11], v[56:57], v[6:7]
	v_pk_fma_f32 v[4:5], v[8:9], v[54:55], v[4:5]
	v_pk_fma_f32 v[2:3], v[10:11], v[26:27], v[2:3]
	v_pk_fma_f32 v[0:1], v[8:9], v[58:59], v[0:1]
	v_pk_fma_f32 v[4:5], v[12:13], v[58:59], v[4:5]
	v_pk_fma_f32 v[6:7], v[14:15], v[26:27], v[6:7]
	v_pk_fma_f32 v[0:1], v[12:13], v[60:61], v[0:1]
	v_pk_fma_f32 v[2:3], v[14:15], v[62:63], v[2:3]
	v_pk_fma_f32 v[6:7], v[18:19], v[62:63], v[6:7]
	v_pk_fma_f32 v[4:5], v[16:17], v[60:61], v[4:5]
	v_pk_fma_f32 v[2:3], v[18:19], v[70:71], v[2:3]
	v_pk_fma_f32 v[0:1], v[16:17], v[68:69], v[0:1]
	ds_write_b128 v101, v[4:7] offset:544
	v_cvt_pk_bf16_f32 v4, v4, v5
	v_cvt_pk_bf16_f32 v5, v6, v7
	ds_write_b64 v28, v[4:5] offset:288
	ds_write_b128 v102, v[0:3]
	v_cvt_pk_bf16_f32 v0, v0, v1
	v_cvt_pk_bf16_f32 v1, v2, v3
	v_add_u32_e32 v2, v96, v99
	ds_write_b64 v2, v[0:1]
	s_waitcnt lgkmcnt(0)
	s_barrier
	ds_read_b128 v[48:51], v103
	ds_read_b128 v[0:3], v109
	s_waitcnt lgkmcnt(0)
	v_mfma_f32_32x32x16_bf16 v[16:31], v[48:51], v[0:3], 0
	ds_read_b128 v[0:3], v109 offset:8192
	ds_read_b128 v[56:59], v103 offset:32
	ds_read_b128 v[52:55], v109 offset:1024
	v_add_u32_e32 v78, 0x1a00, v104
	s_waitcnt lgkmcnt(2)
	v_mfma_f32_32x32x16_bf16 v[0:15], v[48:51], v[0:3], 0
	s_waitcnt lgkmcnt(0)
	v_mfma_f32_32x32x16_bf16 v[16:31], v[56:59], v[52:55], v[16:31]
	ds_read_b128 v[52:55], v109 offset:9216
	s_waitcnt lgkmcnt(0)
	v_mfma_f32_32x32x16_bf16 v[0:15], v[56:59], v[52:55], v[0:15]
	ds_read_b128 v[60:63], v103 offset:64
	ds_read_b128 v[68:71], v109 offset:2048
	ds_read_b128 v[52:55], v103 offset:96
	ds_read2_b32 v[76:77], v104 offset1:68
	ds_read2_b32 v[80:81], v104 offset0:136 offset1:204
	ds_read2_b32 v[74:75], v72 offset0:32 offset1:100
	ds_read2_b32 v[82:83], v72 offset0:168 offset1:236
	ds_read_b128 v[110:113], v109 offset:10240
	s_waitcnt lgkmcnt(6)
	v_mfma_f32_32x32x16_bf16 v[16:31], v[60:63], v[68:71], v[16:31]
	v_add_u32_e32 v68, 0x1000, v104
	ds_read2_b32 v[70:71], v68 offset0:64 offset1:132
	v_add_u32_e32 v68, 0x1200, v104
	ds_read2_b32 v[72:73], v68 offset0:72 offset1:140
	v_add_u32_e32 v68, 0x1800, v104
	s_waitcnt lgkmcnt(2)
	v_mfma_f32_32x32x16_bf16 v[0:15], v[60:63], v[110:113], v[0:15]
	ds_read2_b32 v[68:69], v68 offset0:96 offset1:164
	ds_read_b128 v[110:113], v109 offset:3072
	ds_read2_b32 v[78:79], v78 offset0:104 offset1:172
	s_waitcnt lgkmcnt(1)
	v_mfma_f32_32x32x16_bf16 v[16:31], v[52:55], v[110:113], v[16:31]
	v_add_u32_e32 v110, 64, v114
	ds_read_b128 v[112:115], v109 offset:11264
	v_cmp_lt_i32_e32 vcc, v116, v110
	s_nop 1
	v_cndmask_b32_e32 v110, v180, v116, vcc
	v_lshlrev_b32_e32 v110, 2, v110
	s_nop 4
	v_fmamk_f32 v17, v17, 0xbfb8aa3b, v84
	v_exp_f32_e32 v17, v17
	v_fmamk_f32 v18, v18, 0xbfb8aa3b, v84
	v_exp_f32_e32 v18, v18
	v_add_f32_e32 v17, 1.0, v17
	v_rcp_f32_e32 v17, v17
	v_fmamk_f32 v19, v19, 0xbfb8aa3b, v84
	v_add_f32_e32 v18, 1.0, v18
	v_rcp_f32_e32 v111, v18
	v_mul_f32_e32 v17, v92, v17
	v_fmamk_f32 v20, v20, 0xbfb8aa3b, v84
	s_waitcnt lgkmcnt(0)
	v_mfma_f32_32x32x16_bf16 v[0:15], v[52:55], v[112:115], v[0:15]
	ds_read_b128 v[226:229], v109 offset:16384
	ds_read_b128 v[230:233], v109 offset:24576
	ds_read_b128 v[234:237], v109 offset:17408
	ds_read_b128 v[238:241], v109 offset:25600
	v_exp_f32_e32 v18, v17
	v_mul_f32_e32 v17, v92, v111
	v_exp_f32_e32 v19, v19
	v_exp_f32_e32 v111, v20
	v_exp_f32_e32 v20, v17
	v_add_f32_e32 v17, 1.0, v19
	v_add_f32_e32 v19, 1.0, v111
	v_rcp_f32_e32 v19, v19
	s_nop 2
	s_nop 0
	s_waitcnt lgkmcnt(3)
	v_mfma_f32_32x32x16_bf16 v[156:171], v[48:51], v[226:229], 0
	s_waitcnt lgkmcnt(2)
	v_mfma_f32_32x32x16_bf16 v[210:225], v[48:51], v[230:233], 0
	ds_read_b128 v[226:229], v109 offset:18432
	ds_read_b128 v[230:233], v109 offset:26624
	v_fmamk_f32 v4, v4, 0xbfb8aa3b, v85
	v_exp_f32_e32 v4, v4
	v_mul_f32_e32 v19, v92, v19
	v_exp_f32_e32 v111, v19
	v_add_f32_e32 v4, 1.0, v4
	v_rcp_f32_e32 v19, v4
	v_rcp_f32_e32 v17, v17
	v_fma_f32 v4, -v111, v111, 1.0
	v_sqrt_f32_e64 v112, |v4|
	v_mul_f32_e32 v4, v92, v17
	v_fmamk_f32 v5, v5, 0xbfb8aa3b, v85
	v_mul_f32_e32 v17, v19, v112
	v_fmamk_f32 v19, v21, 0xbfb8aa3b, v84
	v_exp_f32_e32 v19, v19
	v_exp_f32_e32 v5, v5
	v_fmamk_f32 v7, v7, 0xbfb8aa3b, v85
	v_add_f32_e32 v19, 1.0, v19
	v_rcp_f32_e32 v19, v19
	v_add_f32_e32 v5, 1.0, v5
	v_rcp_f32_e32 v5, v5
	v_exp_f32_e32 v7, v7
	v_mul_f32_e32 v19, v92, v19
	v_exp_f32_e32 v114, v19
	v_fmamk_f32 v19, v22, 0xbfb8aa3b, v84
	v_exp_f32_e32 v19, v19
	v_fma_f32 v21, -v114, v114, 1.0
	v_sqrt_f32_e64 v21, |v21|
	v_add_f32_e32 v19, 1.0, v19
	v_rcp_f32_e32 v19, v19
	v_fmamk_f32 v8, v8, 0xbfb8aa3b, v85
	v_mul_f32_e32 v5, v5, v21
	v_fmamk_f32 v21, v23, 0xbfb8aa3b, v84
	v_exp_f32_e32 v21, v21
	v_add_f32_e32 v7, 1.0, v7
	v_mul_f32_e32 v19, v92, v19
	s_waitcnt lgkmcnt(3)
	v_mfma_f32_32x32x16_bf16 v[156:171], v[56:59], v[234:237], v[156:171]
	s_waitcnt lgkmcnt(2)
	v_mfma_f32_32x32x16_bf16 v[210:225], v[56:59], v[238:241], v[210:225]
	ds_read_b128 v[234:237], v109 offset:19456
	ds_read_b128 v[238:241], v109 offset:27648
	v_add_f32_e32 v21, 1.0, v21
	v_rcp_f32_e32 v21, v21
	v_rcp_f32_e32 v7, v7
	v_exp_f32_e32 v8, v8
	v_fmamk_f32 v6, v6, 0xbfb8aa3b, v85
	v_mul_f32_e32 v21, v92, v21
	v_exp_f32_e32 v116, v21
	v_fmamk_f32 v21, v24, 0xbfb8aa3b, v84
	v_fma_f32 v22, -v116, v116, 1.0
	v_sqrt_f32_e64 v22, |v22|
	v_exp_f32_e32 v115, v19
	v_exp_f32_e32 v6, v6
	v_exp_f32_e32 v21, v21
	v_mul_f32_e32 v118, v7, v22
	v_add_f32_e32 v7, 1.0, v8
	v_fmamk_f32 v8, v25, 0xbfb8aa3b, v84
	v_fma_f32 v19, -v115, v115, 1.0
	v_exp_f32_e32 v8, v8
	v_add_f32_e32 v6, 1.0, v6
	v_add_f32_e32 v21, 1.0, v21
	v_rcp_f32_e32 v6, v6
	v_sqrt_f32_e64 v19, |v19|
	v_rcp_f32_e32 v21, v21
	v_add_f32_e32 v8, 1.0, v8
	v_rcp_f32_e32 v8, v8
	v_mul_f32_e32 v117, v6, v19
	v_mul_f32_e32 v6, v92, v21
	v_exp_f32_e32 v6, v6
	v_fmamk_f32 v9, v9, 0xbfb8aa3b, v85
	v_mul_f32_e32 v8, v92, v8
	v_exp_f32_e32 v9, v9
	v_exp_f32_e32 v8, v8
	v_rcp_f32_e32 v23, v7
	v_fma_f32 v7, -v6, v6, 1.0
	v_sqrt_f32_e64 v25, |v7|
	s_waitcnt lgkmcnt(3)
	v_mfma_f32_32x32x16_bf16 v[156:171], v[60:63], v[226:229], v[156:171]
	s_waitcnt lgkmcnt(2)
	v_mfma_f32_32x32x16_bf16 v[210:225], v[60:63], v[230:233], v[210:225]
	v_add_f32_e32 v7, 1.0, v9
	v_rcp_f32_e32 v22, v7
	v_fma_f32 v7, -v8, v8, 1.0
	v_sqrt_f32_e64 v24, |v7|
	v_fmamk_f32 v7, v26, 0xbfb8aa3b, v84
	v_exp_f32_e32 v7, v7
	v_pk_mul_f32 v[24:25], v[22:23], v[24:25]
	v_fmamk_f32 v9, v10, 0xbfb8aa3b, v85
	v_add_f32_e32 v7, 1.0, v7
	v_rcp_f32_e32 v7, v7
	v_exp_f32_e32 v9, v9
	v_fmamk_f32 v11, v11, 0xbfb8aa3b, v85
	v_mul_f32_e32 v7, v92, v7
	v_exp_f32_e32 v23, v7
	v_fmamk_f32 v7, v27, 0xbfb8aa3b, v84
	v_exp_f32_e32 v7, v7
	v_fma_f32 v10, -v23, v23, 1.0
	v_add_f32_e32 v9, 1.0, v9
	v_add_f32_e32 v7, 1.0, v7
	v_rcp_f32_e32 v7, v7
	v_fmamk_f32 v12, v12, 0xbfb8aa3b, v85
	v_rcp_f32_e32 v9, v9
	v_sqrt_f32_e64 v10, |v10|
	v_mul_f32_e32 v7, v92, v7
	v_exp_f32_e32 v21, v7
	v_fmamk_f32 v7, v28, 0xbfb8aa3b, v84
	v_exp_f32_e32 v7, v7
	v_exp_f32_e32 v11, v11
	v_exp_f32_e32 v12, v12
	v_add_f32_e32 v7, 1.0, v7
	v_rcp_f32_e32 v7, v7
	v_mul_f32_e32 v10, v9, v10
	v_add_f32_e32 v9, 1.0, v11
	v_fma_f32 v11, -v21, v21, 1.0
	v_mul_f32_e32 v7, v92, v7
	s_waitcnt lgkmcnt(1)
	v_mfma_f32_32x32x16_bf16 v[156:171], v[52:55], v[234:237], v[156:171]
	s_waitcnt lgkmcnt(0)
	v_mfma_f32_32x32x16_bf16 v[210:225], v[52:55], v[238:241], v[210:225]
	v_exp_f32_e32 v7, v7
	v_add_f32_e32 v12, 1.0, v12
	v_rcp_f32_e32 v9, v9
	v_fma_f32 v19, -v7, v7, 1.0
	v_sqrt_f32_e64 v22, |v19|
	v_fmamk_f32 v19, v29, 0xbfb8aa3b, v84
	v_sqrt_f32_e64 v11, |v11|
	v_rcp_f32_e32 v12, v12
	v_exp_f32_e32 v26, v19
	v_mul_f32_e32 v19, v9, v11
	v_mul_f32_e32 v9, v12, v22
	v_mul_f32_e32 v27, v68, v9
	v_add_f32_e32 v9, 1.0, v26
	v_fmamk_f32 v12, v30, 0xbfb8aa3b, v84
	v_rcp_f32_e32 v9, v9
	v_exp_f32_e32 v12, v12
	v_fmamk_f32 v11, v13, 0xbfb8aa3b, v85
	v_mul_f32_e32 v9, v92, v9
	v_add_f32_e32 v12, 1.0, v12
	v_exp_f32_e32 v9, v9
	v_rcp_f32_e32 v12, v12
	v_fmamk_f32 v16, v16, 0xbfb8aa3b, v84
	v_fma_f32 v13, -v9, v9, 1.0
	v_mul_f32_e32 v12, v92, v12
	v_sqrt_f32_e64 v22, |v13|
	v_exp_f32_e32 v13, v12
	v_fmamk_f32 v12, v31, 0xbfb8aa3b, v84
	v_exp_f32_e32 v12, v12
	v_exp_f32_e32 v16, v16
	v_exp_f32_e32 v11, v11
	v_add_f32_e32 v12, 1.0, v12
	v_rcp_f32_e32 v12, v12
	v_add_f32_e32 v16, 1.0, v16
	v_rcp_f32_e32 v16, v16
	v_fmamk_f32 v15, v15, 0xbfb8aa3b, v85
	v_mul_f32_e32 v12, v92, v12
	v_exp_f32_e32 v29, v12
	v_fmamk_f32 v14, v14, 0xbfb8aa3b, v85
	v_exp_f32_e32 v15, v15
	v_mul_f32_e32 v16, v92, v16
	v_fma_f32 v26, -v13, v13, 1.0
	v_add_f32_e32 v11, 1.0, v11
	v_exp_f32_e32 v14, v14
	v_fmamk_f32 v0, v0, 0xbfb8aa3b, v85
	v_exp_f32_e32 v16, v16
	v_rcp_f32_e32 v11, v11
	v_sqrt_f32_e64 v12, |v26|
	v_fma_f32 v26, -v29, v29, 1.0
	v_add_f32_e32 v15, 1.0, v15
	v_fmamk_f32 v1, v1, 0xbfb8aa3b, v85
	v_exp_f32_e32 v0, v0
	v_rcp_f32_e32 v15, v15
	v_sqrt_f32_e64 v26, |v26|
	v_add_f32_e32 v14, 1.0, v14
	v_fmamk_f32 v2, v2, 0xbfb8aa3b, v85
	v_exp_f32_e32 v1, v1
	v_rcp_f32_e32 v14, v14
	v_mul_f32_e32 v30, v11, v22
	v_fma_f32 v22, -v16, v16, 1.0
	v_exp_f32_e32 v2, v2
	v_add_f32_e32 v0, 1.0, v0
	v_mul_f32_e32 v31, v15, v26
	v_fma_f32 v15, -v18, v18, 1.0
	v_rcp_f32_e32 v0, v0
	v_sqrt_f32_e64 v22, |v22|
	v_add_f32_e32 v1, 1.0, v1
	v_mul_f32_e32 v14, v14, v12
	v_fma_f32 v12, -v20, v20, 1.0
	v_rcp_f32_e32 v1, v1
	v_sqrt_f32_e64 v15, |v15|
	v_fmamk_f32 v3, v3, 0xbfb8aa3b, v85
	v_add_f32_e32 v2, 1.0, v2
	v_exp_f32_e32 v4, v4
	v_rcp_f32_e32 v2, v2
	v_sqrt_f32_e64 v12, |v12|
	v_mul_f32_e32 v0, v0, v22
	v_exp_f32_e32 v3, v3
	v_mul_f32_e32 v0, v76, v0
	v_mul_f32_e32 v1, v1, v15
	v_mul_f32_e32 v0, v18, v0
	v_fmac_f32_e32 v0, v77, v1
	v_fma_f32 v11, -v4, v4, 1.0
	v_mul_f32_e32 v2, v2, v12
	v_mul_f32_e32 v0, v20, v0
	v_add_f32_e32 v3, 1.0, v3
	v_fmac_f32_e32 v0, v80, v2
	v_mul_f32_e32 v17, v74, v17
	v_rcp_f32_e32 v3, v3
	v_sqrt_f32_e64 v11, |v11|
	v_mul_f32_e32 v15, v4, v0
	v_mul_f32_e32 v0, v111, v114
	v_mul_f32_e32 v1, v115, v116
	v_mov_b32_e32 v112, v71
	v_mov_b32_e32 v113, v70
	v_mul_f32_e32 v0, v0, v1
	v_mul_f32_e32 v1, v114, v17
	v_pk_mul_f32 v[24:25], v[112:113], v[24:25]
	v_fmac_f32_e32 v1, v75, v5
	v_mul_f32_e32 v1, v115, v1
	v_fmac_f32_e32 v24, v8, v25
	v_mul_f32_e32 v3, v3, v11
	v_fmac_f32_e32 v1, v82, v117
	v_mov_b32_e32 v22, v72
	v_mov_b32_e32 v11, v24
	v_mul_f32_e32 v2, v72, v10
	v_fmac_f32_e32 v15, v81, v3
	v_mul_f32_e32 v26, v116, v1
	v_pk_fma_f32 v[2:3], v[22:23], v[10:11], v[2:3] op_sel_hi:[1,1,0]
	v_mul_f32_e32 v1, v9, v27
	v_mov_b32_e32 v17, v73
	v_mov_b32_e32 v5, v3
	v_fmac_f32_e32 v1, v69, v30
	v_pk_mul_f32 v[10:11], v[16:17], v[18:19]
	v_pk_mul_f32 v[2:3], v[20:21], v[4:5]
	v_mov_b32_e32 v12, v23
	v_mov_b32_e32 v28, v21
	v_mul_f32_e32 v1, v13, v1
	v_pk_mul_f32 v[4:5], v[10:11], v[2:3]
	v_pk_fma_f32 v[10:11], v[16:17], v[18:19], v[2:3]
	v_pk_mul_f32 v[2:3], v[6:7], v[8:9]
	v_pk_mul_f32 v[6:7], v[12:13], v[28:29]
	v_fmac_f32_e32 v1, v78, v14
	v_pk_mul_f32 v[2:3], v[2:3], v[6:7]
	v_mul_f32_e32 v7, v29, v1
	v_fmac_f32_e32 v26, v83, v118
	v_fmac_f32_e32 v7, v79, v31
	ds_bpermute_b32 v14, v110, v4
	ds_bpermute_b32 v16, v110, v15
	ds_bpermute_b32 v12, v110, v0
	ds_bpermute_b32 v6, v110, v26
	ds_bpermute_b32 v1, v110, v2
	ds_bpermute_b32 v13, v110, v11
	ds_bpermute_b32 v8, v110, v3
	ds_bpermute_b32 v9, v110, v7
	s_and_saveexec_b64 s[46:47], s[42:43]
	s_cbranch_execz .LBB0_353
	v_fmac_f32_e32 v15, 0, v4
	s_waitcnt lgkmcnt(6)
	v_fmac_f32_e32 v16, v15, v14
	v_fmac_f32_e32 v26, v0, v16
	s_waitcnt lgkmcnt(4)
	v_fmac_f32_e32 v6, v26, v12
	v_mul_f32_e32 v15, v2, v6
	v_pk_mul_f32 v[4:5], v[4:5], v[14:15]
	v_pk_add_f32 v[10:11], v[10:11], v[14:15]
	s_waitcnt lgkmcnt(3)
	v_mov_b32_e32 v6, v1
	v_mov_b32_e32 v10, v4
	v_pk_mul_f32 v[4:5], v[0:1], v[4:5]
	s_waitcnt lgkmcnt(2)
	v_pk_fma_f32 v[10:11], v[0:1], v[10:11], v[12:13]
	v_pk_mul_f32 v[4:5], v[4:5], v[12:13]
	v_mov_b32_e32 v0, v1
	v_mov_b32_e32 v5, v11
	v_pk_mul_f32 v[10:11], v[2:3], v[4:5]
	v_pk_fma_f32 v[4:5], v[2:3], v[4:5], v[6:7]
	v_pk_mul_f32 v[0:1], v[10:11], v[0:1]
	s_waitcnt lgkmcnt(0)
	v_pk_mov_b32 v[2:3], v[2:3], v[8:9] op_sel:[1,0]
	v_mov_b32_e32 v4, v0
	v_pk_mul_f32 v[0:1], v[2:3], v[0:1]
	v_pk_fma_f32 v[2:3], v[2:3], v[4:5], v[8:9]
	v_pk_mul_f32 v[0:1], v[0:1], v[8:9]
	s_nop 0
	v_mov_b32_e32 v1, v3
	ds_write_b64 v97, v[0:1]
.LBB0_353:
	s_or_b64 exec, exec, s[46:47]
	s_waitcnt lgkmcnt(0)
	v_mov_b32_e32 v48, v77
	v_fmamk_f32 v17, v157, 0xbfb8aa3b, v86
	v_exp_f32_e32 v17, v17
	v_fmamk_f32 v16, v156, 0xbfb8aa3b, v86
	v_exp_f32_e32 v16, v16
	v_add_f32_e32 v17, 1.0, v17
	v_rcp_f32_e32 v17, v17
	v_fmamk_f32 v4, v214, 0xbfb8aa3b, v87
	v_exp_f32_e32 v4, v4
	v_mul_f32_e32 v17, v93, v17
	v_exp_f32_e32 v49, v17
	v_fmamk_f32 v17, v158, 0xbfb8aa3b, v86
	v_exp_f32_e32 v17, v17
	v_add_f32_e32 v4, 1.0, v4
	v_rcp_f32_e32 v4, v4
	v_fmamk_f32 v5, v215, 0xbfb8aa3b, v87
	v_add_f32_e32 v17, 1.0, v17
	v_rcp_f32_e32 v17, v17
	v_exp_f32_e32 v5, v5
	v_fmamk_f32 v8, v218, 0xbfb8aa3b, v87
	v_mul_f32_e32 v17, v93, v17
	v_exp_f32_e32 v18, v17
	v_fmamk_f32 v17, v159, 0xbfb8aa3b, v86
	v_exp_f32_e32 v17, v17
	v_add_f32_e32 v5, 1.0, v5
	v_exp_f32_e32 v8, v8
	v_add_f32_e32 v17, 1.0, v17
	v_rcp_f32_e32 v17, v17
	v_fmamk_f32 v6, v216, 0xbfb8aa3b, v87
	v_add_f32_e32 v8, 1.0, v8
	v_fmamk_f32 v7, v217, 0xbfb8aa3b, v87
	v_mul_f32_e32 v17, v93, v17
	v_exp_f32_e32 v50, v17
	v_fmamk_f32 v17, v160, 0xbfb8aa3b, v86
	v_exp_f32_e32 v17, v17
	v_exp_f32_e32 v6, v6
	v_add_f32_e32 v17, 1.0, v17
	v_rcp_f32_e32 v17, v17
	v_exp_f32_e32 v7, v7
	v_add_f32_e32 v6, 1.0, v6
	v_rcp_f32_e32 v6, v6
	v_mul_f32_e32 v17, v93, v17
	v_exp_f32_e32 v53, v17
	v_add_f32_e32 v7, 1.0, v7
	v_rcp_f32_e32 v7, v7
	v_fmamk_f32 v9, v219, 0xbfb8aa3b, v87
	v_fma_f32 v17, -v53, v53, 1.0
	v_sqrt_f32_e64 v17, |v17|
	v_exp_f32_e32 v9, v9
	v_fmamk_f32 v10, v220, 0xbfb8aa3b, v87
	v_mul_f32_e32 v55, v4, v17
	v_fmamk_f32 v4, v161, 0xbfb8aa3b, v86
	v_exp_f32_e32 v4, v4
	v_rcp_f32_e32 v17, v5
	v_rcp_f32_e32 v21, v8
	v_add_f32_e32 v9, 1.0, v9
	v_add_f32_e32 v4, 1.0, v4
	v_rcp_f32_e32 v4, v4
	v_rcp_f32_e32 v9, v9
	v_exp_f32_e32 v10, v10
	v_mul_f32_e32 v4, v93, v4
	v_exp_f32_e32 v5, v4
	v_add_f32_e32 v10, 1.0, v10
	v_rcp_f32_e32 v10, v10
	v_add_f32_e32 v16, 1.0, v16
	v_fma_f32 v4, -v5, v5, 1.0
	v_sqrt_f32_e64 v4, |v4|
	v_fmamk_f32 v3, v213, 0xbfb8aa3b, v87
	v_fmamk_f32 v2, v212, 0xbfb8aa3b, v87
	v_fmamk_f32 v1, v211, 0xbfb8aa3b, v87
	v_mul_f32_e32 v20, v17, v4
	v_fmamk_f32 v4, v162, 0xbfb8aa3b, v86
	v_exp_f32_e32 v4, v4
	v_rcp_f32_e32 v16, v16
	v_add_f32_e32 v4, 1.0, v4
	v_rcp_f32_e32 v4, v4
	v_exp_f32_e32 v3, v3
	v_exp_f32_e32 v2, v2
	v_mul_f32_e32 v4, v93, v4
	v_exp_f32_e32 v4, v4
	v_exp_f32_e32 v1, v1
	v_mul_f32_e32 v16, v93, v16
	v_fma_f32 v17, -v4, v4, 1.0
	v_sqrt_f32_e64 v22, |v17|
	v_fmamk_f32 v17, v163, 0xbfb8aa3b, v86
	v_exp_f32_e32 v17, v17
	v_add_f32_e32 v3, 1.0, v3
	v_add_f32_e32 v2, 1.0, v2
	v_add_f32_e32 v1, 1.0, v1
	v_add_f32_e32 v17, 1.0, v17
	v_rcp_f32_e32 v17, v17
	v_fmamk_f32 v0, v210, 0xbfb8aa3b, v87
	v_exp_f32_e32 v16, v16
	v_rcp_f32_e32 v3, v3
	v_mul_f32_e32 v17, v93, v17
	v_exp_f32_e32 v17, v17
	v_rcp_f32_e32 v2, v2
	v_rcp_f32_e32 v1, v1
	v_fma_f32 v19, -v17, v17, 1.0
	v_sqrt_f32_e64 v23, |v19|
	v_fmamk_f32 v19, v164, 0xbfb8aa3b, v86
	v_exp_f32_e32 v19, v19
	v_pk_mul_f32 v[6:7], v[6:7], v[22:23]
	v_exp_f32_e32 v0, v0
	v_pk_mul_f32 v[6:7], v[82:83], v[6:7]
	v_add_f32_e32 v19, 1.0, v19
	v_rcp_f32_e32 v19, v19
	v_add_f32_e32 v0, 1.0, v0
	v_rcp_f32_e32 v0, v0
	v_fmac_f32_e32 v6, v4, v7
	v_mul_f32_e32 v8, v93, v19
	v_exp_f32_e32 v8, v8
	s_nop 0
	v_fma_f32 v19, -v8, v8, 1.0
	v_sqrt_f32_e64 v19, |v19|
	s_nop 0
	v_mul_f32_e32 v22, v21, v19
	v_fmamk_f32 v19, v165, 0xbfb8aa3b, v86
	v_exp_f32_e32 v19, v19
	v_mov_b32_e32 v21, v6
	v_add_f32_e32 v19, 1.0, v19
	v_rcp_f32_e32 v19, v19
	s_nop 0
	v_mul_f32_e32 v19, v93, v19
	v_exp_f32_e32 v54, v19
	s_nop 0
	v_fma_f32 v19, -v54, v54, 1.0
	v_sqrt_f32_e64 v19, |v19|
	s_nop 0
	v_mul_f32_e32 v23, v9, v19
	v_fmamk_f32 v9, v166, 0xbfb8aa3b, v86
	v_exp_f32_e32 v9, v9
	v_mov_b32_e32 v19, v16
	v_add_f32_e32 v9, 1.0, v9
	v_rcp_f32_e32 v9, v9
	s_nop 0
	v_mul_f32_e32 v9, v93, v9
	v_exp_f32_e32 v52, v9
	s_nop 0
	v_fma_f32 v9, -v52, v52, 1.0
	v_sqrt_f32_e64 v9, |v9|
	s_nop 0
	v_mul_f32_e32 v24, v10, v9
	v_fmamk_f32 v9, v167, 0xbfb8aa3b, v86
	v_exp_f32_e32 v9, v9
	v_fmamk_f32 v10, v221, 0xbfb8aa3b, v87
	v_exp_f32_e32 v10, v10
	v_add_f32_e32 v9, 1.0, v9
	v_rcp_f32_e32 v9, v9
	v_add_f32_e32 v10, 1.0, v10
	v_rcp_f32_e32 v11, v10
	v_mul_f32_e32 v9, v93, v9
	v_exp_f32_e32 v10, v9
	s_nop 0
	v_fma_f32 v9, -v10, v10, 1.0
	v_sqrt_f32_e64 v9, |v9|
	s_nop 0
	v_mul_f32_e32 v9, v11, v9
	v_mul_f32_e32 v25, v73, v9
	v_fmamk_f32 v9, v168, 0xbfb8aa3b, v86
	v_exp_f32_e32 v9, v9
	v_fmamk_f32 v11, v222, 0xbfb8aa3b, v87
	v_exp_f32_e32 v11, v11
	v_add_f32_e32 v9, 1.0, v9
	v_rcp_f32_e32 v9, v9
	v_add_f32_e32 v11, 1.0, v11
	v_rcp_f32_e32 v11, v11
	v_mul_f32_e32 v9, v93, v9
	v_exp_f32_e32 v26, v9
	s_nop 0
	v_fma_f32 v9, -v26, v26, 1.0
	v_sqrt_f32_e64 v9, |v9|
	s_nop 0
	v_mul_f32_e32 v27, v11, v9
	v_fmamk_f32 v9, v169, 0xbfb8aa3b, v86
	v_exp_f32_e32 v9, v9
	v_fmamk_f32 v11, v223, 0xbfb8aa3b, v87
	v_exp_f32_e32 v11, v11
	v_add_f32_e32 v9, 1.0, v9
	v_rcp_f32_e32 v9, v9
	v_add_f32_e32 v11, 1.0, v11
	v_rcp_f32_e32 v11, v11
	v_mul_f32_e32 v9, v93, v9
	v_exp_f32_e32 v28, v9
	s_nop 0
	v_fma_f32 v9, -v28, v28, 1.0
	v_sqrt_f32_e64 v9, |v9|
	s_nop 0
	v_mul_f32_e32 v29, v11, v9
	v_fmamk_f32 v9, v170, 0xbfb8aa3b, v86
	v_exp_f32_e32 v9, v9
	v_fmamk_f32 v11, v224, 0xbfb8aa3b, v87
	v_exp_f32_e32 v11, v11
	v_add_f32_e32 v9, 1.0, v9
	v_rcp_f32_e32 v9, v9
	v_mov_b32_e32 v14, v49
	v_add_f32_e32 v11, 1.0, v11
	v_rcp_f32_e32 v11, v11
	v_mul_f32_e32 v9, v93, v9
	v_exp_f32_e32 v30, v9
	s_nop 0
	v_fma_f32 v9, -v30, v30, 1.0
	v_sqrt_f32_e64 v9, |v9|
	s_nop 0
	v_mul_f32_e32 v56, v11, v9
	v_fmamk_f32 v9, v171, 0xbfb8aa3b, v86
	v_exp_f32_e32 v9, v9
	v_fmamk_f32 v11, v225, 0xbfb8aa3b, v87
	v_exp_f32_e32 v11, v11
	v_add_f32_e32 v9, 1.0, v9
	v_rcp_f32_e32 v9, v9
	v_add_f32_e32 v11, 1.0, v11
	v_rcp_f32_e32 v11, v11
	v_mul_f32_e32 v9, v93, v9
	v_exp_f32_e32 v31, v9
	s_nop 0
	v_fma_f32 v9, -v31, v31, 1.0
	v_sqrt_f32_e64 v9, |v9|
	s_nop 0
	v_mul_f32_e32 v9, v11, v9
	v_mul_f32_e32 v57, v79, v9
	v_fma_f32 v9, -v50, v50, 1.0
	v_sqrt_f32_e64 v13, |v9|
	v_fma_f32 v9, -v18, v18, 1.0
	v_sqrt_f32_e64 v12, |v9|
	v_fma_f32 v9, -v49, v49, 1.0
	v_sqrt_f32_e64 v9, |v9|
	v_pk_mul_f32 v[2:3], v[2:3], v[12:13]
	v_mul_f32_e32 v12, v1, v9
	v_fma_f32 v1, -v16, v16, 1.0
	v_sqrt_f32_e64 v1, |v1|
	v_pk_mul_f32 v[2:3], v[80:81], v[2:3]
	v_mov_b32_e32 v9, v74
	v_fmac_f32_e32 v2, v18, v3
	v_mul_f32_e32 v15, v0, v1
	v_mov_b32_e32 v13, v2
	v_mul_f32_e32 v0, v77, v12
	v_pk_fma_f32 v[2:3], v[48:49], v[12:13], v[0:1] op_sel_hi:[1,1,0]
	v_mul_f32_e32 v0, v53, v5
	v_mul_f32_e32 v1, v4, v17
	v_mul_f32_e32 v1, v0, v1
	v_mov_b32_e32 v4, v75
	v_mul_f32_e32 v0, v75, v20
	v_pk_fma_f32 v[6:7], v[4:5], v[20:21], v[0:1] op_sel_hi:[1,1,0]
	v_mul_f32_e32 v0, v52, v25
	v_mov_b32_e32 v17, v76
	v_mov_b32_e32 v51, v3
	v_fmac_f32_e32 v0, v72, v24
	v_pk_mul_f32 v[4:5], v[16:17], v[14:15]
	v_pk_mul_f32 v[12:13], v[18:19], v[50:51]
	v_mov_b32_e32 v11, v7
	v_mul_f32_e32 v0, v54, v0
	v_pk_mul_f32 v[2:3], v[4:5], v[12:13]
	v_pk_fma_f32 v[4:5], v[16:17], v[14:15], v[12:13]
	v_pk_mul_f32 v[12:13], v[8:9], v[54:55]
	v_pk_mul_f32 v[10:11], v[52:53], v[10:11]
	v_fmac_f32_e32 v0, v71, v23
	v_pk_mul_f32 v[6:7], v[12:13], v[10:11]
	v_pk_fma_f32 v[10:11], v[8:9], v[54:55], v[10:11]
	v_mul_f32_e32 v12, v8, v0
	v_mul_f32_e32 v0, v26, v28
	v_mul_f32_e32 v8, v30, v31
	v_mul_f32_e32 v14, v0, v8
	v_mul_f32_e32 v0, v30, v57
	v_fmac_f32_e32 v0, v78, v56
	v_mul_f32_e32 v0, v28, v0
	v_fmac_f32_e32 v0, v69, v29
	v_mul_f32_e32 v15, v26, v0
	v_fmac_f32_e32 v12, v70, v22
	v_fmac_f32_e32 v15, v68, v27
	ds_bpermute_b32 v9, v110, v2
	ds_bpermute_b32 v13, v110, v5
	ds_bpermute_b32 v8, v110, v1
	ds_bpermute_b32 v17, v110, v11
	ds_bpermute_b32 v0, v110, v6
	ds_bpermute_b32 v18, v110, v12
	ds_bpermute_b32 v16, v110, v14
	ds_bpermute_b32 v19, v110, v15
	s_and_saveexec_b64 s[46:47], s[42:43]
	s_cbranch_execz .LBB0_355
	s_waitcnt lgkmcnt(0)
	v_fmac_f32_e32 v19, 0, v16
	v_fmac_f32_e32 v15, v19, v14
	v_fmac_f32_e32 v18, v15, v0
	v_fmac_f32_e32 v12, v6, v18
	v_mul_f32_e32 v15, v12, v8
	v_pk_mul_f32 v[18:19], v[14:15], v[16:17]
	v_pk_add_f32 v[14:15], v[14:15], v[16:17]
	v_pk_mul_f32 v[16:17], v[18:19], v[0:1]
	v_mov_b32_e32 v14, v18
	v_pk_mul_f32 v[6:7], v[6:7], v[16:17]
	v_pk_fma_f32 v[10:11], v[14:15], v[0:1], v[10:11]
	v_mov_b32_e32 v0, v1
	v_mov_b32_e32 v7, v11
	v_pk_mul_f32 v[10:11], v[6:7], v[8:9]
	v_mov_b32_e32 v12, v1
	v_pk_mul_f32 v[0:1], v[0:1], v[10:11]
	v_pk_fma_f32 v[6:7], v[6:7], v[8:9], v[12:13]
	v_pk_mov_b32 v[8:9], v[8:9], v[2:3] op_sel:[1,0]
	v_mov_b32_e32 v6, v0
	v_pk_mul_f32 v[0:1], v[0:1], v[8:9]
	s_nop 0
	v_pk_mul_f32 v[0:1], v[2:3], v[0:1]
	v_pk_fma_f32 v[2:3], v[6:7], v[8:9], v[4:5]
	s_nop 0
	v_mov_b32_e32 v1, v3
	ds_write_b64 v97, v[0:1] offset:512
